# merge epilogue: gate-byte loads issued as one batch per half instead of 16 serialized round trips
# speedup vs baseline: 1.0088x; 1.0056x over previous
;     __device__ __forceinline__ bool run(f32x4 (&acc)[2][2][4][2], const Unit& u, int wr, int wc, int fr, int fq) const {
;     ...
;         const unsigned char* gs = gate + (size_t)u.seg * gseg; const bool last = u.seg == 2;
; #pragma unroll
;         for (int ai = 0; ai < 2; ++ai) {
;             u32x2 ga[4][2], gb[4][2];
; #pragma unroll
;             for (int m = 0; m < 4; ++m)
; #pragma unroll
;                 for (int bj = 0; bj < 2; ++bj) { const size_t p = (size_t)(row0 + ai * HALF + m * 16) * ldg + col0 + bj * HALF;
;                     ga[m][bj] = *(const u32x2*)(gs + p); gb[m][bj] = last ? ga[m][bj] : *(const u32x2*)(gs + gseg + p); }
; #pragma unroll
;             for (int m = 0; m < 4; ++m)
; #pragma unroll
;                 for (int bj = 0; bj < 2; ++bj) { const u32x2 a = ga[m][bj], b = gb[m][bj];
;                     float f[8] = {(float)(a.x & 0xffu), (float)((a.x >> 8) & 0xffu), (float)((a.x >> 16) & 0xffu), (float)(a.x >> 24), (float)(a.y & 0xffu), (float)((a.y >> 8) & 0xffu), (float)((a.y >> 16) & 0xffu), (float)(a.y >> 24)};
;                     if (!last) { const float d[8] = {(float)(b.x & 0xffu), (float)((b.x >> 8) & 0xffu), (float)((b.x >> 16) & 0xffu), (float)(b.x >> 24), (float)(b.y & 0xffu), (float)((b.y >> 8) & 0xffu), (float)((b.y >> 16) & 0xffu), (float)(b.y >> 24)};
; #pragma unroll
;                         for (int j = 0; j < 8; ++j) f[j] *= __builtin_amdgcn_rcpf(d[j]); }
.LBB0_1317:
	s_lshl_b32 s5, s5, 8
	s_lshl_b32 s21, s26, 8
	s_or_b32 s20, s5, s42
	s_ashr_i32 s5, s4, 31
	s_add_i32 s21, s21, s31
	v_or_b32_e32 v156, s20, v143
	s_lshl_b64 s[6:7], s[4:5], 11
	v_readlane_b32 s14, v253, 59
	v_or_b32_e32 v210, s21, v141
	v_readlane_b32 s15, v253, 60
	s_add_u32 s14, s14, s6
	v_ashrrev_i32_e32 v157, 31, v156
	s_addc_u32 s15, s15, s7
	v_mad_i64_i32 v[150:151], s[6:7], v210, s77, v[156:157]
	v_lshl_add_u64 v[230:231], s[14:15], 0, v[150:151]
	v_or_b32_e32 v2, 16, v210
	v_mad_i64_i32 v[232:233], s[16:17], v2, s77, v[156:157]
	v_lshl_add_u64 v[232:233], s[14:15], 0, v[232:233]
	v_or_b32_e32 v2, 32, v210
	v_mad_i64_i32 v[234:235], s[16:17], v2, s77, v[156:157]
	v_lshl_add_u64 v[234:235], s[14:15], 0, v[234:235]
	v_or_b32_e32 v2, 48, v210
	v_mad_i64_i32 v[236:237], s[16:17], v2, s77, v[156:157]
	v_lshl_add_u64 v[236:237], s[14:15], 0, v[236:237]
	s_cmp_eq_u32 s4, 2
	s_cselect_b64 s[18:19], -1, 0
	s_cmp_lg_u32 s4, 2
	s_cselect_b64 s[4:5], -1, 0
	v_cndmask_b32_e64 v2, 0, 1, s[4:5]
	v_cmp_ne_u32_e64 s[6:7], 1, v2
	v_or_b32_e32 v2, 48, v210
	global_load_dwordx2 v[194:195], v[230:231], off
	global_load_dwordx2 v[192:193], v[230:231], off offset:128
	global_load_dwordx2 v[188:189], v[232:233], off
	global_load_dwordx2 v[184:185], v[232:233], off offset:128
	global_load_dwordx2 v[168:169], v[234:235], off
	global_load_dwordx2 v[166:167], v[234:235], off offset:128
	global_load_dwordx2 v[162:163], v[236:237], off
	global_load_dwordx2 v[160:161], v[236:237], off offset:128
	s_and_b64 vcc, exec, s[18:19]
	s_cbranch_vccnz .Lmg1_last
	global_load_dwordx2 v[150:151], v[230:231], off offset:2048
	global_load_dwordx2 v[190:191], v[230:231], off offset:2176
	global_load_dwordx2 v[186:187], v[232:233], off offset:2048
	global_load_dwordx2 v[170:171], v[232:233], off offset:2176
	global_load_dwordx2 v[154:155], v[234:235], off offset:2048
	global_load_dwordx2 v[164:165], v[234:235], off offset:2176
	global_load_dwordx2 v[152:153], v[236:237], off offset:2048
	global_load_dwordx2 v[158:159], v[236:237], off offset:2176
	s_waitcnt vmcnt(0)
	s_branch .Lmg1_join
.Lmg1_last:
	s_waitcnt vmcnt(0)
	v_mov_b64_e32 v[150:151], v[194:195]
	v_mov_b64_e32 v[190:191], v[192:193]
	v_mov_b64_e32 v[186:187], v[188:189]
	v_mov_b64_e32 v[170:171], v[184:185]
	v_mov_b64_e32 v[154:155], v[168:169]
	v_mov_b64_e32 v[164:165], v[166:167]
	v_mov_b64_e32 v[152:153], v[162:163]
	v_mov_b64_e32 v[158:159], v[160:161]
.Lmg1_join:
.LBB0_1333:
	v_cvt_f32_ubyte1_e32 v197, v194
	v_cvt_f32_ubyte0_e32 v196, v194
	v_cvt_f32_ubyte3_e32 v199, v194
	v_cvt_f32_ubyte2_e32 v198, v194
	v_cvt_f32_ubyte1_e32 v201, v195
	v_cvt_f32_ubyte0_e32 v200, v195
	v_cvt_f32_ubyte3_e32 v205, v195
	v_cvt_f32_ubyte2_e32 v204, v195
	s_mov_b64 s[16:17], -1
	s_and_b64 vcc, exec, s[4:5]
	s_cbranch_vccz .LBB0_1335
	v_cvt_f32_ubyte0_e32 v2, v150
	v_cvt_f32_ubyte1_e32 v172, v150
	v_cvt_f32_ubyte2_e32 v173, v150
	v_cvt_f32_ubyte3_e32 v174, v150
	v_cvt_f32_ubyte0_e32 v175, v151
	v_cvt_f32_ubyte1_e32 v176, v151
	v_cvt_f32_ubyte2_e32 v177, v151
	v_cvt_f32_ubyte3_e32 v178, v151
	v_rcp_iflag_f32_e32 v150, v2
	v_rcp_iflag_f32_e32 v151, v172
	v_rcp_iflag_f32_e32 v172, v173
	v_rcp_iflag_f32_e32 v173, v174
	v_rcp_iflag_f32_e32 v174, v175
	v_rcp_iflag_f32_e32 v175, v176
	v_rcp_iflag_f32_e32 v176, v177
	v_rcp_iflag_f32_e32 v177, v178
	v_pk_mul_f32 v[208:209], v[150:151], v[196:197]
	v_pk_mul_f32 v[206:207], v[172:173], v[198:199]
	v_pk_mul_f32 v[202:203], v[174:175], v[200:201]
	v_pk_mul_f32 v[194:195], v[176:177], v[204:205]
	s_mov_b64 s[16:17], 0

;     __device__ __forceinline__ bool run(f32x4 (&acc)[2][2][4][2], const Unit& u, int wr, int wc, int fr, int fq) const {
;     ...
;         for (int ai = 0; ai < 2; ++ai) {
;             u32x2 ga[4][2], gb[4][2];
; #pragma unroll
;             for (int m = 0; m < 4; ++m)
; #pragma unroll
;                 for (int bj = 0; bj < 2; ++bj) { const size_t p = (size_t)(row0 + ai * HALF + m * 16) * ldg + col0 + bj * HALF;
;                     ga[m][bj] = *(const u32x2*)(gs + p); gb[m][bj] = last ? ga[m][bj] : *(const u32x2*)(gs + gseg + p); }
; #pragma unroll
;             for (int m = 0; m < 4; ++m)
; #pragma unroll
;                 for (int bj = 0; bj < 2; ++bj) { const u32x2 a = ga[m][bj], b = gb[m][bj];
;                     float f[8] = {(float)(a.x & 0xffu), (float)((a.x >> 8) & 0xffu), (float)((a.x >> 16) & 0xffu), (float)(a.x >> 24), (float)(a.y & 0xffu), (float)((a.y >> 8) & 0xffu), (float)((a.y >> 16) & 0xffu), (float)(a.y >> 24)};
;                     if (!last) { const float d[8] = {(float)(b.x & 0xffu), (float)((b.x >> 8) & 0xffu), (float)((b.x >> 16) & 0xffu), (float)(b.x >> 24), (float)(b.y & 0xffu), (float)((b.y >> 8) & 0xffu), (float)((b.y >> 16) & 0xffu), (float)(b.y >> 24)};
; #pragma unroll
;                         for (int j = 0; j < 8; ++j) f[j] *= __builtin_amdgcn_rcpf(d[j]); }
.LBB0_1381:
	v_add_u32_e32 v151, 0x80, v210
	s_waitcnt vmcnt(0)
	v_mad_i64_i32 v[230:231], s[16:17], v151, s77, v[156:157]
	v_lshl_add_u64 v[230:231], s[14:15], 0, v[230:231]
	v_add_u32_e32 v151, 0x90, v210
	v_mad_i64_i32 v[232:233], s[16:17], v151, s77, v[156:157]
	v_lshl_add_u64 v[232:233], s[14:15], 0, v[232:233]
	v_add_u32_e32 v151, 0xa0, v210
	v_mad_i64_i32 v[234:235], s[16:17], v151, s77, v[156:157]
	v_lshl_add_u64 v[234:235], s[14:15], 0, v[234:235]
	v_add_u32_e32 v151, 0xb0, v210
	v_mad_i64_i32 v[236:237], s[16:17], v151, s77, v[156:157]
	v_lshl_add_u64 v[236:237], s[14:15], 0, v[236:237]
	global_load_dwordx2 v[200:201], v[230:231], off
	global_load_dwordx2 v[194:195], v[230:231], off offset:128
	global_load_dwordx2 v[190:191], v[232:233], off
	global_load_dwordx2 v[186:187], v[232:233], off offset:128
	global_load_dwordx2 v[170:171], v[234:235], off
	global_load_dwordx2 v[166:167], v[234:235], off offset:128
	global_load_dwordx2 v[162:163], v[236:237], off
	global_load_dwordx2 v[158:159], v[236:237], off offset:128
	s_and_b64 vcc, exec, s[6:7]
	s_cbranch_vccnz .Lmg2_last
	global_load_dwordx2 v[196:197], v[230:231], off offset:2048
	global_load_dwordx2 v[192:193], v[230:231], off offset:2176
	global_load_dwordx2 v[188:189], v[232:233], off offset:2048
	global_load_dwordx2 v[184:185], v[232:233], off offset:2176
	global_load_dwordx2 v[168:169], v[234:235], off offset:2048
	global_load_dwordx2 v[164:165], v[234:235], off offset:2176
	global_load_dwordx2 v[160:161], v[236:237], off offset:2048
	global_load_dwordx2 v[156:157], v[236:237], off offset:2176
	s_waitcnt vmcnt(0)
	s_branch .Lmg2_join
.Lmg2_last:
	s_waitcnt vmcnt(0)
	v_mov_b64_e32 v[196:197], v[200:201]
	v_mov_b64_e32 v[192:193], v[194:195]
	v_mov_b64_e32 v[188:189], v[190:191]
	v_mov_b64_e32 v[184:185], v[186:187]
	v_mov_b64_e32 v[168:169], v[170:171]
	v_mov_b64_e32 v[164:165], v[166:167]
	v_mov_b64_e32 v[160:161], v[162:163]
	v_mov_b64_e32 v[156:157], v[158:159]
.Lmg2_join:
.LBB0_1397:
	v_cvt_f32_ubyte1_e32 v199, v200
	v_cvt_f32_ubyte0_e32 v198, v200
	v_cvt_f32_ubyte3_e32 v203, v200
	v_cvt_f32_ubyte2_e32 v202, v200
	v_cvt_f32_ubyte1_e32 v205, v201
	v_cvt_f32_ubyte0_e32 v204, v201
	v_cvt_f32_ubyte3_e32 v209, v201
	v_cvt_f32_ubyte2_e32 v208, v201
	s_and_b64 vcc, exec, s[6:7]
	s_mov_b64 s[14:15], -1
	s_cbranch_vccnz .LBB0_1399
	v_cvt_f32_ubyte0_e32 v151, v196
	v_cvt_f32_ubyte1_e32 v153, v196
	v_cvt_f32_ubyte2_e32 v155, v196
	v_cvt_f32_ubyte3_e32 v175, v196
	v_cvt_f32_ubyte0_e32 v176, v197
	v_cvt_f32_ubyte1_e32 v177, v197
	v_cvt_f32_ubyte2_e32 v178, v197
	v_cvt_f32_ubyte3_e32 v179, v197
	v_rcp_iflag_f32_e32 v172, v151
	v_rcp_iflag_f32_e32 v173, v153
	v_rcp_iflag_f32_e32 v174, v155
	v_rcp_iflag_f32_e32 v175, v175
	v_rcp_iflag_f32_e32 v176, v176
	v_rcp_iflag_f32_e32 v177, v177
	v_rcp_iflag_f32_e32 v178, v178
	v_rcp_iflag_f32_e32 v179, v179
	v_pk_mul_f32 v[212:213], v[172:173], v[198:199]
	v_pk_mul_f32 v[210:211], v[174:175], v[202:203]
	v_pk_mul_f32 v[206:207], v[176:177], v[204:205]
	v_pk_mul_f32 v[200:201], v[178:179], v[208:209]
	s_mov_b64 s[14:15], 0
